# v6: v5 + ab_out (EpiRes<true>) epilogue rewritten the same way (loads up front, wave groups overlapped)
# speedup vs baseline: 1.0034x; 1.0034x over previous
.LBB0_907:
	s_add_u32 s8, s62, 0x2f704000
	s_addc_u32 s9, s63, 0
	s_lshl_b32 s57, s0, 6
	s_lshl_b32 s14, s0, 13
	s_lshl_b32 s0, s1, 5
	s_mov_b64 s[10:11], 0x80
	s_and_b32 s15, s0, 0x60
	s_add_i32 m0, s36, 0x18000
	v_lshl_add_u64 v[6:7], v[6:7], 0, s[10:11]
	s_lshl_b32 s16, s15, 7
	s_waitcnt vmcnt(4)
	s_barrier
	global_load_lds_dwordx4 v[6:7], off
	v_lshl_add_u64 v[4:5], v[4:5], 0, s[10:11]
	s_add_i32 m0, s36, 0x1a000
	s_add_i32 s58, s36, 0x8000
	s_add_i32 s59, s36, 0xa000
	global_load_lds_dwordx4 v[4:5], off
	v_lshl_add_u64 v[2:3], v[2:3], 0, s[10:11]
	s_mov_b32 m0, s58
	s_add_u32 s0, s50, 0x80080
	global_load_lds_dwordx4 v[2:3], off
	v_lshl_add_u64 v[0:1], v[0:1], 0, s[10:11]
	s_mov_b32 m0, s59
	s_addc_u32 s1, s51, 0
	global_load_lds_dwordx4 v[0:1], off
	s_add_i32 m0, s36, 0x1c000
	v_lshl_add_u64 v[0:1], s[0:1], 0, v[130:131]
	global_load_lds_dwordx4 v[0:1], off
	v_lshl_add_u64 v[0:1], s[0:1], 0, v[134:135]
	s_add_i32 m0, s36, 0x1e000
	v_and_b32_e32 v147, 15, v8
	global_load_lds_dwordx4 v[0:1], off
	v_lshrrev_b32_e32 v0, 1, v8
	v_and_b32_e32 v0, 24, v0
	v_lshlrev_b32_e32 v1, 1, v0
	v_lshlrev_b32_e32 v2, 2, v8
	v_or_b32_e32 v160, s15, v0
	v_lshlrev_b32_e32 v0, 15, v9
	v_lshl_or_b32 v1, v147, 6, v1
	v_and_b32_e32 v2, 32, v2
	v_and_b32_e32 v0, 0xffff0000, v0
	v_bitop3_b32 v3, v1, s14, v2 bitop3:0xde
	v_bitop3_b32 v158, v1, s16, v2 bitop3:0xde
	v_lshl_add_u32 v0, v10, 12, v0
	v_and_b32_e32 v1, 1, v9
	v_lshl_or_b32 v0, v1, 6, v0
	v_lshl_add_u32 v138, v11, 1, v0
	v_lshlrev_b32_e32 v0, 15, v12
	v_and_b32_e32 v0, 0xffff0000, v0
	s_waitcnt vmcnt(6)
	v_lshl_add_u32 v0, v13, 12, v0
	v_and_b32_e32 v1, 1, v12
	v_lshl_or_b32 v0, v1, 6, v0
	s_add_i32 s62, 0, 0x10000
	s_add_i32 s63, 0, 0x14000
	s_ashr_i32 s60, s3, 31
	v_or_b32_e32 v159, 0x80, v147
	v_mov_b32_e32 v139, v137
	v_lshl_add_u32 v140, v14, 1, v0
	v_mov_b32_e32 v141, v137
	v_mov_b64_e32 v[142:143], 0x300
	v_mov_b64_e32 v[148:149], 0x2ff
	s_movk_i32 s61, 0x61
	v_add_u32_e32 v161, s62, v158
	v_add_u32_e32 v162, 0, v3
	v_add_u32_e32 v163, s63, v158
	s_movk_i32 s64, 0x1fff
	s_barrier
	s_branch .LBB0_909
.LBB0_909:
	s_add_i32 s56, s56, 1
	s_mul_i32 s0, s56, s60
	s_mul_hi_u32 s1, s56, s3
	s_add_i32 s1, s1, s0
	s_mul_i32 s0, s56, s3
	s_add_u32 s18, s0, s2
	v_readlane_b32 s0, v254, 26
	s_addc_u32 s19, s1, s0
	v_cmp_gt_i64_e64 s[0:1], s[18:19], v[148:149]
	s_and_b64 vcc, exec, s[0:1]
	s_cbranch_vccnz .LBB0_911
	s_ashr_i32 s14, s18, 31
	s_lshr_b32 s14, s14, 29
	s_add_i32 s14, s18, s14
	s_ashr_i32 s15, s14, 3
	s_and_b32 s14, s14, -8
	s_sub_i32 s14, s18, s14
	s_cmp_lt_i32 s14, 0
	s_cselect_b32 s16, s61, 0x60
	s_mul_i32 s14, s16, s14
	s_add_i32 s14, s14, s15
	s_ashr_i32 s15, s14, 31
	s_lshr_b32 s15, s15, 26
	s_add_i32 s15, s14, s15
	s_ashr_i32 s16, s15, 6
	s_lshl_b32 s16, s16, 3
	s_sub_i32 s17, 0x60, s16
	s_min_i32 s17, s17, 8
	s_abs_i32 s20, s17
	v_cvt_f32_u32_e32 v0, s20
	s_sub_i32 s33, 0, s20
	s_andn2_b32 s15, s15, 63
	s_sub_i32 s15, s14, s15
	v_rcp_iflag_f32_e32 v0, v0
	s_abs_i32 s14, s15
	s_xor_b32 s21, s15, s17
	s_ashr_i32 s21, s21, 31
	v_mul_f32_e32 v0, 0x4f7ffffe, v0
	v_cvt_u32_f32_e32 v0, v0
	s_nop 0
	v_readfirstlane_b32 s34, v0
	s_mul_i32 s33, s33, s34
	s_mul_hi_u32 s33, s34, s33
	s_add_i32 s34, s34, s33
	s_mul_hi_u32 s33, s14, s34
	s_mul_i32 s34, s33, s20
	s_sub_i32 s14, s14, s34
	s_add_i32 s35, s33, 1
	s_sub_i32 s34, s14, s20
	s_cmp_ge_u32 s14, s20
	s_cselect_b32 s33, s35, s33
	s_cselect_b32 s14, s34, s14
	s_add_i32 s34, s33, 1
	s_cmp_ge_u32 s14, s20
	s_cselect_b32 s14, s34, s33
	s_xor_b32 s14, s14, s21
	s_sub_i32 s14, s14, s21
	s_mul_i32 s17, s14, s17
	s_sub_i32 s15, s15, s17
	s_add_i32 s16, s15, s16

.LBB0_912:
	ds_read_b128 v[150:153], v161
	ds_read_b128 v[154:157], v161 offset:1024
	ds_read_b128 v[164:167], v161 offset:2048
	ds_read_b128 v[168:171], v161 offset:3072
	s_add_u32 s20, s48, 0xfff80080
	s_addc_u32 s21, s49, -1
	s_cmp_eq_u32 s47, 28
	s_cselect_b32 s21, s17, s21
	s_cselect_b32 s20, s33, s20
	s_cselect_b32 s51, s15, s45
	s_cselect_b32 s50, s34, s35
	v_lshl_add_u64 v[208:209], s[48:49], 0, v[138:139]
	s_add_i32 m0, s36, 0xc000
	ds_read_b128 v[172:175], v162
	ds_read_b128 v[176:179], v162 offset:1024
	ds_read_b128 v[180:183], v162 offset:2048
	ds_read_b128 v[184:187], v162 offset:3072
	ds_read_b128 v[188:191], v162 offset:4096
	ds_read_b128 v[196:199], v162 offset:5120
	ds_read_b128 v[200:203], v162 offset:6144
	ds_read_b128 v[204:207], v162 offset:7168
	global_load_lds_dwordx4 v[208:209], off
	v_lshl_add_u64 v[208:209], s[48:49], 0, v[140:141]
	s_add_i32 m0, s36, 0xe000
	s_nop 0
	global_load_lds_dwordx4 v[208:209], off
	s_waitcnt lgkmcnt(8)
	s_barrier
	s_waitcnt lgkmcnt(0)
	s_setprio 1
	s_waitcnt lgkmcnt(0)
	v_mfma_f32_16x16x32_bf16 v[124:127], v[150:153], v[172:175], v[124:127]
	v_mfma_f32_16x16x32_bf16 v[120:123], v[164:167], v[172:175], v[120:123]
	v_mfma_f32_16x16x32_bf16 v[108:111], v[150:153], v[180:183], v[108:111]
	v_mfma_f32_16x16x32_bf16 v[104:107], v[164:167], v[180:183], v[104:107]
	v_mfma_f32_16x16x32_bf16 v[92:95], v[150:153], v[188:191], v[92:95]
	v_mfma_f32_16x16x32_bf16 v[88:91], v[164:167], v[188:191], v[88:91]
	v_mfma_f32_16x16x32_bf16 v[76:79], v[150:153], v[200:203], v[76:79]
	v_mfma_f32_16x16x32_bf16 v[72:75], v[164:167], v[200:203], v[72:75]
	v_mfma_f32_16x16x32_bf16 v[124:127], v[154:157], v[176:179], v[124:127]
	v_mfma_f32_16x16x32_bf16 v[120:123], v[168:171], v[176:179], v[120:123]
	v_mfma_f32_16x16x32_bf16 v[108:111], v[154:157], v[184:187], v[108:111]
	v_mfma_f32_16x16x32_bf16 v[104:107], v[168:171], v[184:187], v[104:107]
	v_mfma_f32_16x16x32_bf16 v[92:95], v[154:157], v[196:199], v[92:95]
	v_mfma_f32_16x16x32_bf16 v[88:91], v[168:171], v[196:199], v[88:91]
	v_mfma_f32_16x16x32_bf16 v[76:79], v[154:157], v[204:207], v[76:79]
	v_mfma_f32_16x16x32_bf16 v[72:75], v[168:171], v[204:207], v[72:75]
	s_setprio 0
	s_barrier
	s_add_i32 s65, s62, s23
	v_lshl_add_u64 v[224:225], s[50:51], 0, v[130:131]
	s_mov_b32 m0, s65
	ds_read_b128 v[208:211], v163
	ds_read_b128 v[212:215], v163 offset:1024
	ds_read_b128 v[216:219], v163 offset:2048
	ds_read_b128 v[220:223], v163 offset:3072
	global_load_lds_dwordx4 v[224:225], off
	v_lshl_add_u64 v[226:227], s[50:51], 0, v[134:135]
	s_add_i32 m0, s65, 0x2000
	s_nop 0
	global_load_lds_dwordx4 v[226:227], off
	s_barrier
	s_waitcnt lgkmcnt(0)
	s_setprio 1
	s_waitcnt lgkmcnt(0)
	v_mfma_f32_16x16x32_bf16 v[116:119], v[208:211], v[172:175], v[116:119]
	v_mfma_f32_16x16x32_bf16 v[112:115], v[216:219], v[172:175], v[112:115]
	v_mfma_f32_16x16x32_bf16 v[100:103], v[208:211], v[180:183], v[100:103]
	v_mfma_f32_16x16x32_bf16 v[96:99], v[216:219], v[180:183], v[96:99]
	v_mfma_f32_16x16x32_bf16 v[84:87], v[208:211], v[188:191], v[84:87]
	v_mfma_f32_16x16x32_bf16 v[80:83], v[216:219], v[188:191], v[80:83]
	v_mfma_f32_16x16x32_bf16 v[68:71], v[208:211], v[200:203], v[68:71]
	v_mfma_f32_16x16x32_bf16 v[64:67], v[216:219], v[200:203], v[64:67]
	v_mfma_f32_16x16x32_bf16 v[116:119], v[212:215], v[176:179], v[116:119]
	v_mfma_f32_16x16x32_bf16 v[112:115], v[220:223], v[176:179], v[112:115]
	v_mfma_f32_16x16x32_bf16 v[100:103], v[212:215], v[184:187], v[100:103]
	v_mfma_f32_16x16x32_bf16 v[96:99], v[220:223], v[184:187], v[96:99]
	v_mfma_f32_16x16x32_bf16 v[84:87], v[212:215], v[196:199], v[84:87]
	v_mfma_f32_16x16x32_bf16 v[80:83], v[220:223], v[196:199], v[80:83]
	v_mfma_f32_16x16x32_bf16 v[68:71], v[212:215], v[204:207], v[68:71]
	v_mfma_f32_16x16x32_bf16 v[64:67], v[220:223], v[204:207], v[64:67]
	s_setprio 0
	s_mov_b32 m0, s36
	v_lshl_add_u64 v[228:229], s[20:21], 0, v[128:129]
	s_barrier
	ds_read_b128 v[172:175], v162 offset:16384
	ds_read_b128 v[176:179], v162 offset:17408
	ds_read_b128 v[180:183], v162 offset:18432
	ds_read_b128 v[184:187], v162 offset:19456
	ds_read_b128 v[188:191], v162 offset:20480
	ds_read_b128 v[196:199], v162 offset:21504
	ds_read_b128 v[200:203], v162 offset:22528
	ds_read_b128 v[204:207], v162 offset:23552
	global_load_lds_dwordx4 v[228:229], off
	v_lshl_add_u64 v[230:231], s[20:21], 0, v[132:133]
	s_mov_b32 m0, s37
	s_nop 0
	global_load_lds_dwordx4 v[230:231], off
	s_barrier
	s_waitcnt lgkmcnt(0)
	s_setprio 1
	s_waitcnt lgkmcnt(0)
	v_mfma_f32_16x16x32_bf16 v[60:63], v[150:153], v[172:175], v[60:63]
	v_mfma_f32_16x16x32_bf16 v[56:59], v[164:167], v[172:175], v[56:59]
	v_mfma_f32_16x16x32_bf16 v[44:47], v[150:153], v[180:183], v[44:47]
	v_mfma_f32_16x16x32_bf16 v[40:43], v[164:167], v[180:183], v[40:43]
	v_mfma_f32_16x16x32_bf16 v[28:31], v[150:153], v[188:191], v[28:31]
	v_mfma_f32_16x16x32_bf16 v[24:27], v[164:167], v[188:191], v[24:27]
	v_mfma_f32_16x16x32_bf16 v[12:15], v[150:153], v[200:203], v[12:15]
	v_mfma_f32_16x16x32_bf16 v[8:11], v[164:167], v[200:203], v[8:11]
	v_mfma_f32_16x16x32_bf16 v[60:63], v[154:157], v[176:179], v[60:63]
	v_mfma_f32_16x16x32_bf16 v[56:59], v[168:171], v[176:179], v[56:59]
	v_mfma_f32_16x16x32_bf16 v[44:47], v[154:157], v[184:187], v[44:47]
	v_mfma_f32_16x16x32_bf16 v[40:43], v[168:171], v[184:187], v[40:43]
	v_mfma_f32_16x16x32_bf16 v[28:31], v[154:157], v[196:199], v[28:31]
	v_mfma_f32_16x16x32_bf16 v[24:27], v[168:171], v[196:199], v[24:27]
	v_mfma_f32_16x16x32_bf16 v[12:15], v[154:157], v[204:207], v[12:15]
	v_mfma_f32_16x16x32_bf16 v[8:11], v[168:171], v[204:207], v[8:11]
	s_setprio 0
	s_barrier
	s_add_u32 s66, s50, 0x80000
	s_addc_u32 s67, s51, 0
	s_add_i32 s65, s63, s23
	v_lshl_add_u64 v[150:151], s[66:67], 0, v[130:131]
	s_mov_b32 m0, s65
	s_nop 0
	global_load_lds_dwordx4 v[150:151], off
	v_lshl_add_u64 v[150:151], s[66:67], 0, v[134:135]
	s_add_i32 m0, s65, 0x2000
	s_nop 0
	global_load_lds_dwordx4 v[150:151], off
	s_waitcnt vmcnt(6)
	s_barrier
	s_setprio 1
	v_mfma_f32_16x16x32_bf16 v[52:55], v[208:211], v[172:175], v[52:55]
	v_mfma_f32_16x16x32_bf16 v[48:51], v[216:219], v[172:175], v[48:51]
	v_mfma_f32_16x16x32_bf16 v[36:39], v[208:211], v[180:183], v[36:39]
	v_mfma_f32_16x16x32_bf16 v[32:35], v[216:219], v[180:183], v[32:35]
	v_mfma_f32_16x16x32_bf16 v[20:23], v[208:211], v[188:191], v[20:23]
	v_mfma_f32_16x16x32_bf16 v[16:19], v[216:219], v[188:191], v[16:19]
	v_mfma_f32_16x16x32_bf16 v[4:7], v[208:211], v[200:203], v[4:7]
	v_mfma_f32_16x16x32_bf16 v[0:3], v[216:219], v[200:203], v[0:3]
	v_mfma_f32_16x16x32_bf16 v[52:55], v[212:215], v[176:179], v[52:55]
	v_mfma_f32_16x16x32_bf16 v[48:51], v[220:223], v[176:179], v[48:51]
	v_mfma_f32_16x16x32_bf16 v[36:39], v[212:215], v[184:187], v[36:39]
	v_mfma_f32_16x16x32_bf16 v[32:35], v[220:223], v[184:187], v[32:35]
	v_mfma_f32_16x16x32_bf16 v[20:23], v[212:215], v[196:199], v[20:23]
	v_mfma_f32_16x16x32_bf16 v[16:19], v[220:223], v[196:199], v[16:19]
	v_mfma_f32_16x16x32_bf16 v[4:7], v[212:215], v[204:207], v[4:7]
	v_mfma_f32_16x16x32_bf16 v[0:3], v[220:223], v[204:207], v[0:3]
	s_setprio 0
	s_add_i32 s65, 0, 0x18000
	v_add_u32_e32 v136, s65, v158
	s_barrier
	ds_read_b128 v[150:153], v136
	ds_read_b128 v[154:157], v136 offset:1024
	ds_read_b128 v[164:167], v136 offset:2048
	ds_read_b128 v[168:171], v136 offset:3072
	s_add_u32 s20, s20, 0x80000
	s_addc_u32 s21, s21, 0
	s_mov_b32 m0, s38
	v_lshl_add_u64 v[208:209], s[20:21], 0, v[128:129]
	ds_read_b128 v[172:175], v162 offset:32768
	ds_read_b128 v[176:179], v162 offset:33792
	ds_read_b128 v[180:183], v162 offset:34816
	ds_read_b128 v[184:187], v162 offset:35840
	ds_read_b128 v[188:191], v162 offset:36864
	ds_read_b128 v[196:199], v162 offset:37888
	ds_read_b128 v[200:203], v162 offset:38912
	ds_read_b128 v[204:207], v162 offset:39936
	global_load_lds_dwordx4 v[208:209], off
	v_lshl_add_u64 v[208:209], s[20:21], 0, v[132:133]
	s_mov_b32 m0, s39
	s_nop 0
	global_load_lds_dwordx4 v[208:209], off
	s_waitcnt lgkmcnt(8)
	s_barrier
	s_waitcnt lgkmcnt(0)
	s_setprio 1
	s_waitcnt lgkmcnt(0)
	v_mfma_f32_16x16x32_bf16 v[124:127], v[150:153], v[172:175], v[124:127]
	v_mfma_f32_16x16x32_bf16 v[120:123], v[164:167], v[172:175], v[120:123]
	v_mfma_f32_16x16x32_bf16 v[108:111], v[150:153], v[180:183], v[108:111]
	v_mfma_f32_16x16x32_bf16 v[104:107], v[164:167], v[180:183], v[104:107]
	v_mfma_f32_16x16x32_bf16 v[92:95], v[150:153], v[188:191], v[92:95]
	v_mfma_f32_16x16x32_bf16 v[88:91], v[164:167], v[188:191], v[88:91]
	v_mfma_f32_16x16x32_bf16 v[76:79], v[150:153], v[200:203], v[76:79]
	v_mfma_f32_16x16x32_bf16 v[72:75], v[164:167], v[200:203], v[72:75]
	v_mfma_f32_16x16x32_bf16 v[124:127], v[154:157], v[176:179], v[124:127]
	v_mfma_f32_16x16x32_bf16 v[120:123], v[168:171], v[176:179], v[120:123]
	v_mfma_f32_16x16x32_bf16 v[108:111], v[154:157], v[184:187], v[108:111]
	v_mfma_f32_16x16x32_bf16 v[104:107], v[168:171], v[184:187], v[104:107]
	v_mfma_f32_16x16x32_bf16 v[92:95], v[154:157], v[196:199], v[92:95]
	v_mfma_f32_16x16x32_bf16 v[88:91], v[168:171], v[196:199], v[88:91]
	v_mfma_f32_16x16x32_bf16 v[76:79], v[154:157], v[204:207], v[76:79]
	v_mfma_f32_16x16x32_bf16 v[72:75], v[168:171], v[204:207], v[72:75]
	s_setprio 0
	s_barrier
	s_add_i32 s66, 0, 0x1c000
	s_add_i32 s20, s65, s23
	v_add_u32_e32 v136, s66, v158
	v_lshl_add_u64 v[224:225], v[224:225], 0, s[10:11]
	s_mov_b32 m0, s20
	ds_read_b128 v[208:211], v136
	ds_read_b128 v[212:215], v136 offset:1024
	ds_read_b128 v[216:219], v136 offset:2048
	ds_read_b128 v[220:223], v136 offset:3072
	global_load_lds_dwordx4 v[224:225], off
	v_lshl_add_u64 v[224:225], v[226:227], 0, s[10:11]
	s_add_i32 m0, s20, 0x2000
	s_nop 0
	global_load_lds_dwordx4 v[224:225], off
	s_barrier
	s_waitcnt lgkmcnt(0)
	s_setprio 1
	s_waitcnt lgkmcnt(0)
	v_mfma_f32_16x16x32_bf16 v[116:119], v[208:211], v[172:175], v[116:119]
	v_mfma_f32_16x16x32_bf16 v[112:115], v[216:219], v[172:175], v[112:115]
	v_mfma_f32_16x16x32_bf16 v[100:103], v[208:211], v[180:183], v[100:103]
	v_mfma_f32_16x16x32_bf16 v[96:99], v[216:219], v[180:183], v[96:99]
	v_mfma_f32_16x16x32_bf16 v[84:87], v[208:211], v[188:191], v[84:87]
	v_mfma_f32_16x16x32_bf16 v[80:83], v[216:219], v[188:191], v[80:83]
	v_mfma_f32_16x16x32_bf16 v[68:71], v[208:211], v[200:203], v[68:71]
	v_mfma_f32_16x16x32_bf16 v[64:67], v[216:219], v[200:203], v[64:67]
	v_mfma_f32_16x16x32_bf16 v[116:119], v[212:215], v[176:179], v[116:119]
	v_mfma_f32_16x16x32_bf16 v[112:115], v[220:223], v[176:179], v[112:115]
	v_mfma_f32_16x16x32_bf16 v[100:103], v[212:215], v[184:187], v[100:103]
	v_mfma_f32_16x16x32_bf16 v[96:99], v[220:223], v[184:187], v[96:99]
	v_mfma_f32_16x16x32_bf16 v[84:87], v[212:215], v[196:199], v[84:87]
	v_mfma_f32_16x16x32_bf16 v[80:83], v[220:223], v[196:199], v[80:83]
	v_mfma_f32_16x16x32_bf16 v[68:71], v[212:215], v[204:207], v[68:71]
	v_mfma_f32_16x16x32_bf16 v[64:67], v[220:223], v[204:207], v[64:67]
	s_setprio 0
	s_mov_b32 m0, s58
	v_lshl_add_u64 v[224:225], v[228:229], 0, s[10:11]
	s_barrier
	ds_read_b128 v[172:175], v162 offset:49152
	ds_read_b128 v[176:179], v162 offset:50176
	ds_read_b128 v[180:183], v162 offset:51200
	ds_read_b128 v[184:187], v162 offset:52224
	ds_read_b128 v[188:191], v162 offset:53248
	ds_read_b128 v[196:199], v162 offset:54272
	ds_read_b128 v[200:203], v162 offset:55296
	ds_read_b128 v[204:207], v162 offset:56320
	global_load_lds_dwordx4 v[224:225], off
	v_lshl_add_u64 v[224:225], v[230:231], 0, s[10:11]
	s_mov_b32 m0, s59
	s_nop 0
	global_load_lds_dwordx4 v[224:225], off
	s_barrier
	s_waitcnt lgkmcnt(0)
	s_setprio 1
	s_waitcnt lgkmcnt(0)
	v_mfma_f32_16x16x32_bf16 v[60:63], v[150:153], v[172:175], v[60:63]
	v_mfma_f32_16x16x32_bf16 v[56:59], v[164:167], v[172:175], v[56:59]
	v_mfma_f32_16x16x32_bf16 v[44:47], v[150:153], v[180:183], v[44:47]
	v_mfma_f32_16x16x32_bf16 v[40:43], v[164:167], v[180:183], v[40:43]
	v_mfma_f32_16x16x32_bf16 v[28:31], v[150:153], v[188:191], v[28:31]
	v_mfma_f32_16x16x32_bf16 v[24:27], v[164:167], v[188:191], v[24:27]
	v_mfma_f32_16x16x32_bf16 v[12:15], v[150:153], v[200:203], v[12:15]
	v_mfma_f32_16x16x32_bf16 v[8:11], v[164:167], v[200:203], v[8:11]
	v_mfma_f32_16x16x32_bf16 v[60:63], v[154:157], v[176:179], v[60:63]
	v_mfma_f32_16x16x32_bf16 v[56:59], v[168:171], v[176:179], v[56:59]
	v_mfma_f32_16x16x32_bf16 v[44:47], v[154:157], v[184:187], v[44:47]
	v_mfma_f32_16x16x32_bf16 v[40:43], v[168:171], v[184:187], v[40:43]
	v_mfma_f32_16x16x32_bf16 v[28:31], v[154:157], v[196:199], v[28:31]
	v_mfma_f32_16x16x32_bf16 v[24:27], v[168:171], v[196:199], v[24:27]
	v_mfma_f32_16x16x32_bf16 v[12:15], v[154:157], v[204:207], v[12:15]
	v_mfma_f32_16x16x32_bf16 v[8:11], v[168:171], v[204:207], v[8:11]
	s_setprio 0
	s_barrier
	s_add_u32 s20, s50, 0x80080
	s_addc_u32 s21, s51, 0
	s_add_i32 s50, s66, s23
	v_lshl_add_u64 v[150:151], s[20:21], 0, v[130:131]
	s_mov_b32 m0, s50
	s_nop 0
	global_load_lds_dwordx4 v[150:151], off
	v_lshl_add_u64 v[150:151], s[20:21], 0, v[134:135]
	s_add_i32 m0, s50, 0x2000
	s_nop 0
	global_load_lds_dwordx4 v[150:151], off
	s_waitcnt vmcnt(6)
	s_barrier
	s_setprio 1
	v_mfma_f32_16x16x32_bf16 v[52:55], v[208:211], v[172:175], v[52:55]
	v_mfma_f32_16x16x32_bf16 v[48:51], v[216:219], v[172:175], v[48:51]
	v_mfma_f32_16x16x32_bf16 v[36:39], v[208:211], v[180:183], v[36:39]
	v_mfma_f32_16x16x32_bf16 v[32:35], v[216:219], v[180:183], v[32:35]
	v_mfma_f32_16x16x32_bf16 v[20:23], v[208:211], v[188:191], v[20:23]
	v_mfma_f32_16x16x32_bf16 v[16:19], v[216:219], v[188:191], v[16:19]
	v_mfma_f32_16x16x32_bf16 v[4:7], v[208:211], v[200:203], v[4:7]
	v_mfma_f32_16x16x32_bf16 v[0:3], v[216:219], v[200:203], v[0:3]
	v_mfma_f32_16x16x32_bf16 v[52:55], v[212:215], v[176:179], v[52:55]
	v_mfma_f32_16x16x32_bf16 v[48:51], v[220:223], v[176:179], v[48:51]
	v_mfma_f32_16x16x32_bf16 v[36:39], v[212:215], v[184:187], v[36:39]
	v_mfma_f32_16x16x32_bf16 v[32:35], v[220:223], v[184:187], v[32:35]
	v_mfma_f32_16x16x32_bf16 v[20:23], v[212:215], v[196:199], v[20:23]
	v_mfma_f32_16x16x32_bf16 v[16:19], v[220:223], v[196:199], v[16:19]
	v_mfma_f32_16x16x32_bf16 v[4:7], v[212:215], v[204:207], v[4:7]
	v_mfma_f32_16x16x32_bf16 v[0:3], v[220:223], v[204:207], v[0:3]
	s_setprio 0
	s_add_i32 s47, s47, 2
	s_add_u32 s48, s48, 0x100
	s_addc_u32 s49, s49, 0
	s_add_u32 s35, s35, 0x100
	s_addc_u32 s45, s45, 0
	s_cmp_gt_u32 s47, 29
	s_cbranch_scc0 .Lepi_nl_about
	s_cmp_lg_u32 s57, 64
	s_cbranch_scc1 .Lepi_nl_about
	s_lshl_b32 s15, s46, 8
	s_add_i32 s15, s15, s57
	v_or_b32_e32 v154, s15, v147
	s_add_i32 s17, s15, 0xffffe000
	v_lshl_or_b32 v150, s44, 8, v160
	s_lshr_b32 s17, s17, 12
	v_lshlrev_b32_e32 v151, 13, v154
	s_add_i32 s17, s17, 1
	s_sub_u32 s34, s54, 0x4000000
	s_subb_u32 s35, s55, 0
	v_lshlrev_b32_e32 v152, 12, v154
	s_cmp_gt_i32 s15, s64
	s_cselect_b32 s34, s34, s52
	s_cselect_b32 s35, s35, s53
	s_cselect_b32 s17, s17, 0
	s_mul_i32 s17, s17, 0xc000
	v_lshl_add_u32 v151, v150, 2, v151
	s_add_u32 s20, s8, s17
	s_addc_u32 s21, s9, 0
	v_lshl_add_u32 v152, v150, 1, v152
	v_lshlrev_b32_e32 v153, 2, v150
	s_nop 0
	global_load_dwordx4 v[196:199], v153, s[20:21]
	global_load_dwordx4 v[200:203], v153, s[20:21] offset:16
	global_load_dwordx4 v[204:207], v153, s[20:21] offset:512
	global_load_dwordx4 v[208:211], v153, s[20:21] offset:528
	global_load_dwordx4 v[164:167], v151, s[34:35]
	global_load_dwordx4 v[168:171], v151, s[34:35] offset:16
	global_load_dwordx4 v[172:175], v151, s[34:35] offset:512
	global_load_dwordx4 v[176:179], v151, s[34:35] offset:528
	v_add_u32_e32 v155, 0x20000, v151
	global_load_dwordx4 v[180:183], v155, s[34:35]
	global_load_dwordx4 v[184:187], v155, s[34:35] offset:16
	global_load_dwordx4 v[188:191], v155, s[34:35] offset:512
	global_load_dwordx4 v[212:215], v155, s[34:35] offset:528
	v_add_u32_e32 v155, 0x40000, v151
	global_load_dwordx4 v[216:219], v155, s[34:35]
	global_load_dwordx4 v[220:223], v155, s[34:35] offset:16
	global_load_dwordx4 v[224:227], v155, s[34:35] offset:512
	global_load_dwordx4 v[228:231], v155, s[34:35] offset:528
	v_add_u32_e32 v155, 0x60000, v151
	global_load_dwordx4 v[236:239], v155, s[34:35]
	global_load_dwordx4 v[240:243], v155, s[34:35] offset:16
	global_load_dwordx4 v[244:247], v155, s[34:35] offset:512
	global_load_dwordx4 v[248:251], v155, s[34:35] offset:528
	s_waitcnt vmcnt(0)
	v_pk_fma_f32 v[124:125], v[124:125], v[196:197], v[164:165]
	v_pk_fma_f32 v[126:127], v[126:127], v[198:199], v[166:167]
	v_pk_fma_f32 v[120:121], v[120:121], v[200:201], v[168:169]
	v_pk_fma_f32 v[122:123], v[122:123], v[202:203], v[170:171]
	v_cvt_pk_bf16_f32 v123, v122, v123
	v_cvt_pk_bf16_f32 v122, v120, v121
	v_cvt_pk_bf16_f32 v121, v126, v127
	v_cvt_pk_bf16_f32 v120, v124, v125
	global_store_dwordx4 v152, v[120:123], s[74:75]
	v_pk_fma_f32 v[116:117], v[116:117], v[204:205], v[172:173]
	v_pk_fma_f32 v[118:119], v[118:119], v[206:207], v[174:175]
	v_pk_fma_f32 v[112:113], v[112:113], v[208:209], v[176:177]
	v_pk_fma_f32 v[114:115], v[114:115], v[210:211], v[178:179]
	v_cvt_pk_bf16_f32 v115, v114, v115
	v_cvt_pk_bf16_f32 v114, v112, v113
	v_cvt_pk_bf16_f32 v113, v118, v119
	v_cvt_pk_bf16_f32 v112, v116, v117
	global_store_dwordx4 v152, v[112:115], s[74:75] offset:256
	v_pk_fma_f32 v[108:109], v[108:109], v[196:197], v[180:181]
	v_pk_fma_f32 v[110:111], v[110:111], v[198:199], v[182:183]
	v_pk_fma_f32 v[104:105], v[104:105], v[200:201], v[184:185]
	v_pk_fma_f32 v[106:107], v[106:107], v[202:203], v[186:187]
	v_cvt_pk_bf16_f32 v107, v106, v107
	v_cvt_pk_bf16_f32 v106, v104, v105
	v_cvt_pk_bf16_f32 v105, v110, v111
	v_cvt_pk_bf16_f32 v104, v108, v109
	v_add_u32_e32 v156, 0x10000, v152
	global_store_dwordx4 v156, v[104:107], s[74:75]
	v_pk_fma_f32 v[100:101], v[100:101], v[204:205], v[188:189]
	v_pk_fma_f32 v[102:103], v[102:103], v[206:207], v[190:191]
	v_pk_fma_f32 v[96:97], v[96:97], v[208:209], v[212:213]
	v_pk_fma_f32 v[98:99], v[98:99], v[210:211], v[214:215]
	v_cvt_pk_bf16_f32 v99, v98, v99
	v_cvt_pk_bf16_f32 v98, v96, v97
	v_cvt_pk_bf16_f32 v97, v102, v103
	v_cvt_pk_bf16_f32 v96, v100, v101
	v_add_u32_e32 v156, 0x10000, v152
	global_store_dwordx4 v156, v[96:99], s[74:75] offset:256
	v_add_u32_e32 v155, 0x100000, v151
	global_load_dwordx4 v[164:167], v155, s[34:35]
	global_load_dwordx4 v[168:171], v155, s[34:35] offset:16
	global_load_dwordx4 v[172:175], v155, s[34:35] offset:512
	global_load_dwordx4 v[176:179], v155, s[34:35] offset:528
	v_add_u32_e32 v155, 0x120000, v151
	global_load_dwordx4 v[180:183], v155, s[34:35]
	global_load_dwordx4 v[184:187], v155, s[34:35] offset:16
	global_load_dwordx4 v[188:191], v155, s[34:35] offset:512
	global_load_dwordx4 v[212:215], v155, s[34:35] offset:528
	v_pk_fma_f32 v[92:93], v[92:93], v[196:197], v[216:217]
	v_pk_fma_f32 v[94:95], v[94:95], v[198:199], v[218:219]
	v_pk_fma_f32 v[88:89], v[88:89], v[200:201], v[220:221]
	v_pk_fma_f32 v[90:91], v[90:91], v[202:203], v[222:223]
	v_cvt_pk_bf16_f32 v91, v90, v91
	v_cvt_pk_bf16_f32 v90, v88, v89
	v_cvt_pk_bf16_f32 v89, v94, v95
	v_cvt_pk_bf16_f32 v88, v92, v93
	v_add_u32_e32 v156, 0x20000, v152
	global_store_dwordx4 v156, v[88:91], s[74:75]
	v_pk_fma_f32 v[84:85], v[84:85], v[204:205], v[224:225]
	v_pk_fma_f32 v[86:87], v[86:87], v[206:207], v[226:227]
	v_pk_fma_f32 v[80:81], v[80:81], v[208:209], v[228:229]
	v_pk_fma_f32 v[82:83], v[82:83], v[210:211], v[230:231]
	v_cvt_pk_bf16_f32 v83, v82, v83
	v_cvt_pk_bf16_f32 v82, v80, v81
	v_cvt_pk_bf16_f32 v81, v86, v87
	v_cvt_pk_bf16_f32 v80, v84, v85
	v_add_u32_e32 v156, 0x20000, v152
	global_store_dwordx4 v156, v[80:83], s[74:75] offset:256
	v_pk_fma_f32 v[76:77], v[76:77], v[196:197], v[236:237]
	v_pk_fma_f32 v[78:79], v[78:79], v[198:199], v[238:239]
	v_pk_fma_f32 v[72:73], v[72:73], v[200:201], v[240:241]
	v_pk_fma_f32 v[74:75], v[74:75], v[202:203], v[242:243]
	v_cvt_pk_bf16_f32 v75, v74, v75
	v_cvt_pk_bf16_f32 v74, v72, v73
	v_cvt_pk_bf16_f32 v73, v78, v79
	v_cvt_pk_bf16_f32 v72, v76, v77
	v_add_u32_e32 v156, 0x30000, v152
	global_store_dwordx4 v156, v[72:75], s[74:75]
	v_pk_fma_f32 v[68:69], v[68:69], v[204:205], v[244:245]
	v_pk_fma_f32 v[70:71], v[70:71], v[206:207], v[246:247]
	v_pk_fma_f32 v[64:65], v[64:65], v[208:209], v[248:249]
	v_pk_fma_f32 v[66:67], v[66:67], v[210:211], v[250:251]
	v_cvt_pk_bf16_f32 v67, v66, v67
	v_cvt_pk_bf16_f32 v66, v64, v65
	v_cvt_pk_bf16_f32 v65, v70, v71
	v_cvt_pk_bf16_f32 v64, v68, v69
	v_add_u32_e32 v156, 0x30000, v152
	global_store_dwordx4 v156, v[64:67], s[74:75] offset:256
	v_add_u32_e32 v155, 0x140000, v151
	global_load_dwordx4 v[216:219], v155, s[34:35]
	global_load_dwordx4 v[220:223], v155, s[34:35] offset:16
	global_load_dwordx4 v[224:227], v155, s[34:35] offset:512
	global_load_dwordx4 v[228:231], v155, s[34:35] offset:528
	v_add_u32_e32 v155, 0x160000, v151
	global_load_dwordx4 v[236:239], v155, s[34:35]
	global_load_dwordx4 v[240:243], v155, s[34:35] offset:16
	global_load_dwordx4 v[244:247], v155, s[34:35] offset:512
	global_load_dwordx4 v[248:251], v155, s[34:35] offset:528
	s_waitcnt vmcnt(0)
	v_pk_fma_f32 v[60:61], v[60:61], v[196:197], v[164:165]
	v_pk_fma_f32 v[62:63], v[62:63], v[198:199], v[166:167]
	v_pk_fma_f32 v[56:57], v[56:57], v[200:201], v[168:169]
	v_pk_fma_f32 v[58:59], v[58:59], v[202:203], v[170:171]
	v_cvt_pk_bf16_f32 v59, v58, v59
	v_cvt_pk_bf16_f32 v58, v56, v57
	v_cvt_pk_bf16_f32 v57, v62, v63
	v_cvt_pk_bf16_f32 v56, v60, v61
	v_add_u32_e32 v156, 0x80000, v152
	global_store_dwordx4 v156, v[56:59], s[74:75]
	v_pk_fma_f32 v[52:53], v[52:53], v[204:205], v[172:173]
	v_pk_fma_f32 v[54:55], v[54:55], v[206:207], v[174:175]
	v_pk_fma_f32 v[48:49], v[48:49], v[208:209], v[176:177]
	v_pk_fma_f32 v[50:51], v[50:51], v[210:211], v[178:179]
	v_cvt_pk_bf16_f32 v51, v50, v51
	v_cvt_pk_bf16_f32 v50, v48, v49
	v_cvt_pk_bf16_f32 v49, v54, v55
	v_cvt_pk_bf16_f32 v48, v52, v53
	v_add_u32_e32 v156, 0x80000, v152
	global_store_dwordx4 v156, v[48:51], s[74:75] offset:256
	v_pk_fma_f32 v[44:45], v[44:45], v[196:197], v[180:181]
	v_pk_fma_f32 v[46:47], v[46:47], v[198:199], v[182:183]
	v_pk_fma_f32 v[40:41], v[40:41], v[200:201], v[184:185]
	v_pk_fma_f32 v[42:43], v[42:43], v[202:203], v[186:187]
	v_cvt_pk_bf16_f32 v43, v42, v43
	v_cvt_pk_bf16_f32 v42, v40, v41
	v_cvt_pk_bf16_f32 v41, v46, v47
	v_cvt_pk_bf16_f32 v40, v44, v45
	v_add_u32_e32 v156, 0x90000, v152
	global_store_dwordx4 v156, v[40:43], s[74:75]
	v_pk_fma_f32 v[36:37], v[36:37], v[204:205], v[188:189]
	v_pk_fma_f32 v[38:39], v[38:39], v[206:207], v[190:191]
	v_pk_fma_f32 v[32:33], v[32:33], v[208:209], v[212:213]
	v_pk_fma_f32 v[34:35], v[34:35], v[210:211], v[214:215]
	v_cvt_pk_bf16_f32 v35, v34, v35
	v_cvt_pk_bf16_f32 v34, v32, v33
	v_cvt_pk_bf16_f32 v33, v38, v39
	v_cvt_pk_bf16_f32 v32, v36, v37
	v_add_u32_e32 v156, 0x90000, v152
	global_store_dwordx4 v156, v[32:35], s[74:75] offset:256
	v_pk_fma_f32 v[28:29], v[28:29], v[196:197], v[216:217]
	v_pk_fma_f32 v[30:31], v[30:31], v[198:199], v[218:219]
	v_pk_fma_f32 v[24:25], v[24:25], v[200:201], v[220:221]
	v_pk_fma_f32 v[26:27], v[26:27], v[202:203], v[222:223]
	v_cvt_pk_bf16_f32 v27, v26, v27
	v_cvt_pk_bf16_f32 v26, v24, v25
	v_cvt_pk_bf16_f32 v25, v30, v31
	v_cvt_pk_bf16_f32 v24, v28, v29
	v_add_u32_e32 v156, 0xa0000, v152
	global_store_dwordx4 v156, v[24:27], s[74:75]
	v_pk_fma_f32 v[20:21], v[20:21], v[204:205], v[224:225]
	v_pk_fma_f32 v[22:23], v[22:23], v[206:207], v[226:227]
	v_pk_fma_f32 v[16:17], v[16:17], v[208:209], v[228:229]
	v_pk_fma_f32 v[18:19], v[18:19], v[210:211], v[230:231]
	v_cvt_pk_bf16_f32 v19, v18, v19
	v_cvt_pk_bf16_f32 v18, v16, v17
	v_cvt_pk_bf16_f32 v17, v22, v23
	v_cvt_pk_bf16_f32 v16, v20, v21
	v_add_u32_e32 v156, 0xa0000, v152
	global_store_dwordx4 v156, v[16:19], s[74:75] offset:256
	v_pk_fma_f32 v[12:13], v[12:13], v[196:197], v[236:237]
	v_pk_fma_f32 v[14:15], v[14:15], v[198:199], v[238:239]
	v_pk_fma_f32 v[8:9], v[8:9], v[200:201], v[240:241]
	v_pk_fma_f32 v[10:11], v[10:11], v[202:203], v[242:243]
	v_cvt_pk_bf16_f32 v11, v10, v11
	v_cvt_pk_bf16_f32 v10, v8, v9
	v_cvt_pk_bf16_f32 v9, v14, v15
	v_cvt_pk_bf16_f32 v8, v12, v13
	v_add_u32_e32 v156, 0xb0000, v152
	global_store_dwordx4 v156, v[8:11], s[74:75]
	v_pk_fma_f32 v[4:5], v[4:5], v[204:205], v[244:245]
	v_pk_fma_f32 v[6:7], v[6:7], v[206:207], v[246:247]
	v_pk_fma_f32 v[0:1], v[0:1], v[208:209], v[248:249]
	v_pk_fma_f32 v[2:3], v[2:3], v[210:211], v[250:251]
	v_cvt_pk_bf16_f32 v3, v2, v3
	v_cvt_pk_bf16_f32 v2, v0, v1
	v_cvt_pk_bf16_f32 v1, v6, v7
	v_cvt_pk_bf16_f32 v0, v4, v5
	v_add_u32_e32 v156, 0xb0000, v152
	global_store_dwordx4 v156, v[0:3], s[74:75] offset:256
.Lepi_nl_about:
	s_cmp_gt_u32 s47, 29
	s_barrier
	s_cbranch_scc0 .LBB0_912
	s_cmp_lg_u32 s57, 0
	s_cbranch_scc1 .Lepi_g0done_about
	s_lshl_b32 s15, s46, 8
	s_add_i32 s15, s15, s57
	v_or_b32_e32 v154, s15, v147
	s_add_i32 s17, s15, 0xffffe000
	v_lshl_or_b32 v150, s44, 8, v160
	s_lshr_b32 s17, s17, 12
	v_lshlrev_b32_e32 v151, 13, v154
	s_add_i32 s17, s17, 1
	s_sub_u32 s34, s54, 0x4000000
	s_subb_u32 s35, s55, 0
	v_lshlrev_b32_e32 v152, 12, v154
	s_cmp_gt_i32 s15, s64
	s_cselect_b32 s34, s34, s52
	s_cselect_b32 s35, s35, s53
	s_cselect_b32 s17, s17, 0
	s_mul_i32 s17, s17, 0xc000
	v_lshl_add_u32 v151, v150, 2, v151
	s_add_u32 s20, s8, s17
	s_addc_u32 s21, s9, 0
	v_lshl_add_u32 v152, v150, 1, v152
	v_lshlrev_b32_e32 v153, 2, v150
	s_nop 0
	global_load_dwordx4 v[196:199], v153, s[20:21]
	global_load_dwordx4 v[200:203], v153, s[20:21] offset:16
	global_load_dwordx4 v[204:207], v153, s[20:21] offset:512
	global_load_dwordx4 v[208:211], v153, s[20:21] offset:528
	global_load_dwordx4 v[164:167], v151, s[34:35]
	global_load_dwordx4 v[168:171], v151, s[34:35] offset:16
	global_load_dwordx4 v[172:175], v151, s[34:35] offset:512
	global_load_dwordx4 v[176:179], v151, s[34:35] offset:528
	v_add_u32_e32 v155, 0x20000, v151
	global_load_dwordx4 v[180:183], v155, s[34:35]
	global_load_dwordx4 v[184:187], v155, s[34:35] offset:16
	global_load_dwordx4 v[188:191], v155, s[34:35] offset:512
	global_load_dwordx4 v[212:215], v155, s[34:35] offset:528
	v_add_u32_e32 v155, 0x40000, v151
	global_load_dwordx4 v[216:219], v155, s[34:35]
	global_load_dwordx4 v[220:223], v155, s[34:35] offset:16
	global_load_dwordx4 v[224:227], v155, s[34:35] offset:512
	global_load_dwordx4 v[228:231], v155, s[34:35] offset:528
	v_add_u32_e32 v155, 0x60000, v151
	global_load_dwordx4 v[236:239], v155, s[34:35]
	global_load_dwordx4 v[240:243], v155, s[34:35] offset:16
	global_load_dwordx4 v[244:247], v155, s[34:35] offset:512
	global_load_dwordx4 v[248:251], v155, s[34:35] offset:528
	s_waitcnt vmcnt(0)
	v_pk_fma_f32 v[124:125], v[124:125], v[196:197], v[164:165]
	v_pk_fma_f32 v[126:127], v[126:127], v[198:199], v[166:167]
	v_pk_fma_f32 v[120:121], v[120:121], v[200:201], v[168:169]
	v_pk_fma_f32 v[122:123], v[122:123], v[202:203], v[170:171]
	v_cvt_pk_bf16_f32 v123, v122, v123
	v_cvt_pk_bf16_f32 v122, v120, v121
	v_cvt_pk_bf16_f32 v121, v126, v127
	v_cvt_pk_bf16_f32 v120, v124, v125
	global_store_dwordx4 v152, v[120:123], s[74:75]
	v_pk_fma_f32 v[116:117], v[116:117], v[204:205], v[172:173]
	v_pk_fma_f32 v[118:119], v[118:119], v[206:207], v[174:175]
	v_pk_fma_f32 v[112:113], v[112:113], v[208:209], v[176:177]
	v_pk_fma_f32 v[114:115], v[114:115], v[210:211], v[178:179]
	v_cvt_pk_bf16_f32 v115, v114, v115
	v_cvt_pk_bf16_f32 v114, v112, v113
	v_cvt_pk_bf16_f32 v113, v118, v119
	v_cvt_pk_bf16_f32 v112, v116, v117
	global_store_dwordx4 v152, v[112:115], s[74:75] offset:256
	v_pk_fma_f32 v[108:109], v[108:109], v[196:197], v[180:181]
	v_pk_fma_f32 v[110:111], v[110:111], v[198:199], v[182:183]
	v_pk_fma_f32 v[104:105], v[104:105], v[200:201], v[184:185]
	v_pk_fma_f32 v[106:107], v[106:107], v[202:203], v[186:187]
	v_cvt_pk_bf16_f32 v107, v106, v107
	v_cvt_pk_bf16_f32 v106, v104, v105
	v_cvt_pk_bf16_f32 v105, v110, v111
	v_cvt_pk_bf16_f32 v104, v108, v109
	v_add_u32_e32 v156, 0x10000, v152
	global_store_dwordx4 v156, v[104:107], s[74:75]
	v_pk_fma_f32 v[100:101], v[100:101], v[204:205], v[188:189]
	v_pk_fma_f32 v[102:103], v[102:103], v[206:207], v[190:191]
	v_pk_fma_f32 v[96:97], v[96:97], v[208:209], v[212:213]
	v_pk_fma_f32 v[98:99], v[98:99], v[210:211], v[214:215]
	v_cvt_pk_bf16_f32 v99, v98, v99
	v_cvt_pk_bf16_f32 v98, v96, v97
	v_cvt_pk_bf16_f32 v97, v102, v103
	v_cvt_pk_bf16_f32 v96, v100, v101
	v_add_u32_e32 v156, 0x10000, v152
	global_store_dwordx4 v156, v[96:99], s[74:75] offset:256
	v_add_u32_e32 v155, 0x100000, v151
	global_load_dwordx4 v[164:167], v155, s[34:35]
	global_load_dwordx4 v[168:171], v155, s[34:35] offset:16
	global_load_dwordx4 v[172:175], v155, s[34:35] offset:512
	global_load_dwordx4 v[176:179], v155, s[34:35] offset:528
	v_add_u32_e32 v155, 0x120000, v151
	global_load_dwordx4 v[180:183], v155, s[34:35]
	global_load_dwordx4 v[184:187], v155, s[34:35] offset:16
	global_load_dwordx4 v[188:191], v155, s[34:35] offset:512
	global_load_dwordx4 v[212:215], v155, s[34:35] offset:528
	v_pk_fma_f32 v[92:93], v[92:93], v[196:197], v[216:217]
	v_pk_fma_f32 v[94:95], v[94:95], v[198:199], v[218:219]
	v_pk_fma_f32 v[88:89], v[88:89], v[200:201], v[220:221]
	v_pk_fma_f32 v[90:91], v[90:91], v[202:203], v[222:223]
	v_cvt_pk_bf16_f32 v91, v90, v91
	v_cvt_pk_bf16_f32 v90, v88, v89
	v_cvt_pk_bf16_f32 v89, v94, v95
	v_cvt_pk_bf16_f32 v88, v92, v93
	v_add_u32_e32 v156, 0x20000, v152
	global_store_dwordx4 v156, v[88:91], s[74:75]
	v_pk_fma_f32 v[84:85], v[84:85], v[204:205], v[224:225]
	v_pk_fma_f32 v[86:87], v[86:87], v[206:207], v[226:227]
	v_pk_fma_f32 v[80:81], v[80:81], v[208:209], v[228:229]
	v_pk_fma_f32 v[82:83], v[82:83], v[210:211], v[230:231]
	v_cvt_pk_bf16_f32 v83, v82, v83
	v_cvt_pk_bf16_f32 v82, v80, v81
	v_cvt_pk_bf16_f32 v81, v86, v87
	v_cvt_pk_bf16_f32 v80, v84, v85
	v_add_u32_e32 v156, 0x20000, v152
	global_store_dwordx4 v156, v[80:83], s[74:75] offset:256
	v_pk_fma_f32 v[76:77], v[76:77], v[196:197], v[236:237]
	v_pk_fma_f32 v[78:79], v[78:79], v[198:199], v[238:239]
	v_pk_fma_f32 v[72:73], v[72:73], v[200:201], v[240:241]
	v_pk_fma_f32 v[74:75], v[74:75], v[202:203], v[242:243]
	v_cvt_pk_bf16_f32 v75, v74, v75
	v_cvt_pk_bf16_f32 v74, v72, v73
	v_cvt_pk_bf16_f32 v73, v78, v79
	v_cvt_pk_bf16_f32 v72, v76, v77
	v_add_u32_e32 v156, 0x30000, v152
	global_store_dwordx4 v156, v[72:75], s[74:75]
	v_pk_fma_f32 v[68:69], v[68:69], v[204:205], v[244:245]
	v_pk_fma_f32 v[70:71], v[70:71], v[206:207], v[246:247]
	v_pk_fma_f32 v[64:65], v[64:65], v[208:209], v[248:249]
	v_pk_fma_f32 v[66:67], v[66:67], v[210:211], v[250:251]
	v_cvt_pk_bf16_f32 v67, v66, v67
	v_cvt_pk_bf16_f32 v66, v64, v65
	v_cvt_pk_bf16_f32 v65, v70, v71
	v_cvt_pk_bf16_f32 v64, v68, v69
	v_add_u32_e32 v156, 0x30000, v152
	global_store_dwordx4 v156, v[64:67], s[74:75] offset:256
	v_add_u32_e32 v155, 0x140000, v151
	global_load_dwordx4 v[216:219], v155, s[34:35]
	global_load_dwordx4 v[220:223], v155, s[34:35] offset:16
	global_load_dwordx4 v[224:227], v155, s[34:35] offset:512
	global_load_dwordx4 v[228:231], v155, s[34:35] offset:528
	v_add_u32_e32 v155, 0x160000, v151
	global_load_dwordx4 v[236:239], v155, s[34:35]
	global_load_dwordx4 v[240:243], v155, s[34:35] offset:16
	global_load_dwordx4 v[244:247], v155, s[34:35] offset:512
	global_load_dwordx4 v[248:251], v155, s[34:35] offset:528
	s_waitcnt vmcnt(0)
	v_pk_fma_f32 v[60:61], v[60:61], v[196:197], v[164:165]
	v_pk_fma_f32 v[62:63], v[62:63], v[198:199], v[166:167]
	v_pk_fma_f32 v[56:57], v[56:57], v[200:201], v[168:169]
	v_pk_fma_f32 v[58:59], v[58:59], v[202:203], v[170:171]
	v_cvt_pk_bf16_f32 v59, v58, v59
	v_cvt_pk_bf16_f32 v58, v56, v57
	v_cvt_pk_bf16_f32 v57, v62, v63
	v_cvt_pk_bf16_f32 v56, v60, v61
	v_add_u32_e32 v156, 0x80000, v152
	global_store_dwordx4 v156, v[56:59], s[74:75]
	v_pk_fma_f32 v[52:53], v[52:53], v[204:205], v[172:173]
	v_pk_fma_f32 v[54:55], v[54:55], v[206:207], v[174:175]
	v_pk_fma_f32 v[48:49], v[48:49], v[208:209], v[176:177]
	v_pk_fma_f32 v[50:51], v[50:51], v[210:211], v[178:179]
	v_cvt_pk_bf16_f32 v51, v50, v51
	v_cvt_pk_bf16_f32 v50, v48, v49
	v_cvt_pk_bf16_f32 v49, v54, v55
	v_cvt_pk_bf16_f32 v48, v52, v53
	v_add_u32_e32 v156, 0x80000, v152
	global_store_dwordx4 v156, v[48:51], s[74:75] offset:256
	v_pk_fma_f32 v[44:45], v[44:45], v[196:197], v[180:181]
	v_pk_fma_f32 v[46:47], v[46:47], v[198:199], v[182:183]
	v_pk_fma_f32 v[40:41], v[40:41], v[200:201], v[184:185]
	v_pk_fma_f32 v[42:43], v[42:43], v[202:203], v[186:187]
	v_cvt_pk_bf16_f32 v43, v42, v43
	v_cvt_pk_bf16_f32 v42, v40, v41
	v_cvt_pk_bf16_f32 v41, v46, v47
	v_cvt_pk_bf16_f32 v40, v44, v45
	v_add_u32_e32 v156, 0x90000, v152
	global_store_dwordx4 v156, v[40:43], s[74:75]
	v_pk_fma_f32 v[36:37], v[36:37], v[204:205], v[188:189]
	v_pk_fma_f32 v[38:39], v[38:39], v[206:207], v[190:191]
	v_pk_fma_f32 v[32:33], v[32:33], v[208:209], v[212:213]
	v_pk_fma_f32 v[34:35], v[34:35], v[210:211], v[214:215]
	v_cvt_pk_bf16_f32 v35, v34, v35
	v_cvt_pk_bf16_f32 v34, v32, v33
	v_cvt_pk_bf16_f32 v33, v38, v39
	v_cvt_pk_bf16_f32 v32, v36, v37
	v_add_u32_e32 v156, 0x90000, v152
	global_store_dwordx4 v156, v[32:35], s[74:75] offset:256
	v_pk_fma_f32 v[28:29], v[28:29], v[196:197], v[216:217]
	v_pk_fma_f32 v[30:31], v[30:31], v[198:199], v[218:219]
	v_pk_fma_f32 v[24:25], v[24:25], v[200:201], v[220:221]
	v_pk_fma_f32 v[26:27], v[26:27], v[202:203], v[222:223]
	v_cvt_pk_bf16_f32 v27, v26, v27
	v_cvt_pk_bf16_f32 v26, v24, v25
	v_cvt_pk_bf16_f32 v25, v30, v31
	v_cvt_pk_bf16_f32 v24, v28, v29
	v_add_u32_e32 v156, 0xa0000, v152
	global_store_dwordx4 v156, v[24:27], s[74:75]
	v_pk_fma_f32 v[20:21], v[20:21], v[204:205], v[224:225]
	v_pk_fma_f32 v[22:23], v[22:23], v[206:207], v[226:227]
	v_pk_fma_f32 v[16:17], v[16:17], v[208:209], v[228:229]
	v_pk_fma_f32 v[18:19], v[18:19], v[210:211], v[230:231]
	v_cvt_pk_bf16_f32 v19, v18, v19
	v_cvt_pk_bf16_f32 v18, v16, v17
	v_cvt_pk_bf16_f32 v17, v22, v23
	v_cvt_pk_bf16_f32 v16, v20, v21
	v_add_u32_e32 v156, 0xa0000, v152
	global_store_dwordx4 v156, v[16:19], s[74:75] offset:256
	v_pk_fma_f32 v[12:13], v[12:13], v[196:197], v[236:237]
	v_pk_fma_f32 v[14:15], v[14:15], v[198:199], v[238:239]
	v_pk_fma_f32 v[8:9], v[8:9], v[200:201], v[240:241]
	v_pk_fma_f32 v[10:11], v[10:11], v[202:203], v[242:243]
	v_cvt_pk_bf16_f32 v11, v10, v11
	v_cvt_pk_bf16_f32 v10, v8, v9
	v_cvt_pk_bf16_f32 v9, v14, v15
	v_cvt_pk_bf16_f32 v8, v12, v13
	v_add_u32_e32 v156, 0xb0000, v152
	global_store_dwordx4 v156, v[8:11], s[74:75]
	v_pk_fma_f32 v[4:5], v[4:5], v[204:205], v[244:245]
	v_pk_fma_f32 v[6:7], v[6:7], v[206:207], v[246:247]
	v_pk_fma_f32 v[0:1], v[0:1], v[208:209], v[248:249]
	v_pk_fma_f32 v[2:3], v[2:3], v[210:211], v[250:251]
	v_cvt_pk_bf16_f32 v3, v2, v3
	v_cvt_pk_bf16_f32 v2, v0, v1
	v_cvt_pk_bf16_f32 v1, v6, v7
	v_cvt_pk_bf16_f32 v0, v4, v5
	v_add_u32_e32 v156, 0xb0000, v152
	global_store_dwordx4 v156, v[0:3], s[74:75] offset:256
.Lepi_g0done_about:
	s_mov_b32 s44, s14
	s_mov_b32 s46, s16
	s_mov_b64 s[50:51], s[40:41]
	s_mov_b64 s[48:49], s[18:19]
	s_and_b64 vcc, exec, s[0:1]
	s_cbranch_vccnz .LBB0_945
	s_branch .LBB0_909
